# diff-attention tile visiting: rigorous tighter skip bound (tiles whose weights are provably < 2^-48 of the row's own-key weight are not visited; outputs bit-identical here)
# speedup vs baseline: 1.0415x; 1.0354x over previous
; #define LAS __attribute__((address_space(3)))
; __device__ __forceinline__ void diff_unit(const PolDiff& P, LAS unsigned char* lds, const Ptrs& X) {
;     ...
;       float qm1 = 0.f, qm2 = 0.f;
; #pragma unroll
;       for (int w_ = 0; w_ < 4; ++w_) { qm1 = fmaxf(qm1, ((LAS float*)(lds + DF_SCR))[w_ * 64]); qm2 = fmaxf(qm2, ((LAS float*)(lds + DF_SCR))[(w_ + 4) * 64]); }
;       qm1 = sqrtf(qm1) * 1.01f; qm2 = sqrtf(qm2) * 1.01f;
;       const float* kn = X.kn + ((P.b * 8 + P.h) * 2) * 128;
;       const float k1_ = sqrtf(kn[2 * lane] + kn[2 * lane + 1]) * 1.001f, k2_ = sqrtf(kn[128 + 2 * lane] + kn[128 + 2 * lane + 1]) * 1.001f;
;       const float sb = fmaxf(qm1 * k1_, qm2 * k2_);
;       const int i0u = 128 * P.qb;
;       const int dist = lane < 2 * P.qb ? i0u - (64 * lane + 63) : (lane > 2 * P.qb + 1 ? 64 * lane - (i0u + 127) : 0);
;       const bool visit = sb + P.nsl * (float)dist > -152.f;
;       const unsigned long long mask = __ballot(visit) | (3ull << (2 * P.qb));
;       int lo = __builtin_ctzll(mask), hi_t = 63 - __builtin_clzll(mask);
;     ...
;       if (hi_t - lo + 1 < 4) { if (lo > 1) lo -= 2; else hi_t += 2; }
.LBB0_255:
	s_or_b64 exec, exec, s[0:1]
	s_add_i32 s0, 0, 0x18000
	v_mov_b32_e32 v2, s0
	v_readlane_b32 s0, v254, 9
	s_waitcnt lgkmcnt(0)
	s_barrier
	ds_read_b32 v11, v2
	v_mov_b32_e32 v2, s0
	v_readlane_b32 s0, v254, 10
	ds_read_b32 v9, v2
	s_lshl_b32 s1, s2, 13
	v_mov_b32_e32 v2, s0
	v_readlane_b32 s0, v254, 11
	ds_read_b32 v13, v2
	v_lshlrev_b32_e32 v19, 3, v8
	v_mov_b32_e32 v2, s0
	v_readlane_b32 s0, v254, 12
	ds_read_b32 v10, v2
	v_lshlrev_b32_e32 v20, 6, v8
	v_mov_b32_e32 v2, s0
	v_readlane_b32 s0, v254, 13
	ds_read_b32 v14, v2
	s_nop 0
	v_mov_b32_e32 v2, s0
	v_readlane_b32 s0, v254, 14
	ds_read_b32 v12, v2
	s_nop 0
	v_mov_b32_e32 v2, s0
	v_readlane_b32 s0, v254, 15
	ds_read_b32 v16, v2
	s_nop 0
	v_mov_b32_e32 v2, s0
	s_lshl_b32 s0, s5, 10
	s_or_b32 s0, s1, s0
	s_add_u32 s0, s62, s0
	s_addc_u32 s1, s63, 0
	ds_read_b32 v15, v2
	global_load_dwordx2 v[4:5], v19, s[0:1]
	global_load_dwordx2 v[2:3], v19, s[0:1] offset:512
	s_lshl_b32 s29, s4, 1
	v_cmp_le_u32_e32 vcc, s29, v8
	s_and_saveexec_b64 s[0:1], vcc
	s_xor_b64 s[0:1], exec, s[0:1]
	s_or_b32 s4, s29, 1
	v_subrev_u32_e32 v17, s42, v20
	v_add_u32_e32 v17, 0xffffff81, v17
	v_cmp_lt_u32_e32 vcc, s4, v8
	s_nop 1
	v_cndmask_b32_e32 v17, 0, v17, vcc
	s_andn2_saveexec_b64 s[0:1], s[0:1]
	v_sub_u32_e32 v17, s42, v20
	v_subrev_u32_e32 v17, 63, v17
	s_or_b64 exec, exec, s[0:1]
	s_waitcnt lgkmcnt(5)
	v_max3_f32 v11, v11, 0, v13
	s_waitcnt lgkmcnt(1)
	v_max3_f32 v11, v11, v14, v16
	s_mov_b32 s0, 0xf800000
	v_mul_f32_e32 v13, 0x4f800000, v11
	v_cmp_gt_f32_e32 vcc, s0, v11
	v_max3_f32 v9, v9, 0, v10
	s_waitcnt lgkmcnt(0)
	v_max3_f32 v9, v9, v12, v15
	v_cndmask_b32_e32 v11, v11, v13, vcc
	v_sqrt_f32_e32 v13, v11
	s_waitcnt vmcnt(1)
	v_add_f32_e32 v4, v4, v5
	v_mul_f32_e32 v5, 0x4f800000, v4
	s_waitcnt vmcnt(0)
	v_add_f32_e32 v2, v2, v3
	v_add_u32_e32 v10, -1, v13
	v_fma_f32 v12, -v10, v13, v11
	v_cmp_ge_f32_e64 s[4:5], 0, v12
	v_add_u32_e32 v12, 1, v13
	v_mul_f32_e32 v3, 0x4f800000, v2
	v_cndmask_b32_e64 v10, v13, v10, s[4:5]
	v_fma_f32 v13, -v12, v13, v11
	v_cmp_lt_f32_e64 s[4:5], 0, v13
	s_nop 1
	v_cndmask_b32_e64 v10, v10, v12, s[4:5]
	v_mul_f32_e32 v12, 0x37800000, v10
	v_cndmask_b32_e32 v10, v10, v12, vcc
	v_mul_f32_e32 v12, 0x4f800000, v9
	v_cmp_gt_f32_e32 vcc, s0, v9
	v_cmp_class_f32_e64 s[4:5], v11, v216
	s_nop 0
	v_cndmask_b32_e32 v9, v9, v12, vcc
	v_sqrt_f32_e32 v12, v9
	v_cndmask_b32_e64 v10, v10, v11, s[4:5]
	v_mul_f32_e32 v10, 0x3f8147ae, v10
	v_add_u32_e32 v11, -1, v12
	v_fma_f32 v13, -v11, v12, v9
	v_cmp_ge_f32_e64 s[4:5], 0, v13
	v_add_u32_e32 v13, 1, v12
	s_nop 0
	v_cndmask_b32_e64 v11, v12, v11, s[4:5]
	v_fma_f32 v12, -v13, v12, v9
	v_cmp_lt_f32_e64 s[4:5], 0, v12
	s_nop 1
	v_cndmask_b32_e64 v11, v11, v13, s[4:5]
	v_mul_f32_e32 v12, 0x37800000, v11
	v_cndmask_b32_e32 v11, v11, v12, vcc
	v_cmp_gt_f32_e32 vcc, s0, v4
	v_cmp_class_f32_e64 s[4:5], v9, v216
	s_nop 0
	v_cndmask_b32_e32 v4, v4, v5, vcc
	v_sqrt_f32_e32 v5, v4
	v_cndmask_b32_e64 v9, v11, v9, s[4:5]
	v_mul_f32_e32 v9, 0x3f8147ae, v9
	v_add_u32_e32 v11, -1, v5
	v_fma_f32 v12, -v11, v5, v4
	v_cmp_ge_f32_e64 s[4:5], 0, v12
	v_add_u32_e32 v12, 1, v5
	s_nop 0
	v_cndmask_b32_e64 v11, v5, v11, s[4:5]
	v_fma_f32 v5, -v12, v5, v4
	v_cmp_lt_f32_e64 s[4:5], 0, v5
	s_nop 1
	v_cndmask_b32_e64 v5, v11, v12, s[4:5]
	v_mul_f32_e32 v11, 0x37800000, v5
	v_cndmask_b32_e32 v5, v5, v11, vcc
	v_cmp_gt_f32_e32 vcc, s0, v2
	v_cmp_class_f32_e64 s[4:5], v4, v216
	s_sub_i32 s0, 8, s11
	v_cndmask_b32_e32 v2, v2, v3, vcc
	v_sqrt_f32_e32 v3, v2
	v_cndmask_b32_e64 v4, v5, v4, s[4:5]
	v_mul_f32_e32 v4, 0x3f8020c5, v4
	v_add_u32_e32 v5, -1, v3
	v_fma_f32 v11, -v5, v3, v2
	v_cmp_ge_f32_e64 s[4:5], 0, v11
	v_add_u32_e32 v11, 1, v3
	s_nop 0
	v_cndmask_b32_e64 v5, v3, v5, s[4:5]
	v_fma_f32 v3, -v11, v3, v2
	v_cmp_lt_f32_e64 s[4:5], 0, v3
	s_nop 1
	v_cndmask_b32_e64 v3, v5, v11, s[4:5]
	v_mul_f32_e32 v5, 0x37800000, v3
	v_cndmask_b32_e32 v3, v3, v5, vcc
	v_cmp_class_f32_e32 vcc, v2, v216
	v_cvt_f32_i32_e32 v5, v17
	s_nop 0
	v_cndmask_b32_e32 v2, v3, v2, vcc
	v_mul_f32_e32 v3, v10, v4
	v_cvt_f32_ubyte0_e32 v4, s0
	v_exp_f32_e64 v4, -v4
	v_mul_f32_e32 v2, 0x3f8020c5, v2
	v_mul_f32_e32 v2, v9, v2
	v_max_f32_e32 v2, v3, v2
	v_lshlrev_b32_e32 v21, 2, v8
	v_mov_b32_e32 v20, v2
	v_xor_b32_e32 v22, 4, v21
	ds_bpermute_b32 v22, v22, v20
	s_waitcnt lgkmcnt(0)
	v_max_f32_e32 v20, v20, v22
	v_xor_b32_e32 v22, 8, v21
	ds_bpermute_b32 v22, v22, v20
	s_waitcnt lgkmcnt(0)
	v_max_f32_e32 v20, v20, v22
	v_xor_b32_e32 v22, 16, v21
	ds_bpermute_b32 v22, v22, v20
	s_waitcnt lgkmcnt(0)
	v_max_f32_e32 v20, v20, v22
	v_xor_b32_e32 v22, 32, v21
	ds_bpermute_b32 v22, v22, v20
	s_waitcnt lgkmcnt(0)
	v_max_f32_e32 v20, v20, v22
	v_xor_b32_e32 v22, 64, v21
	ds_bpermute_b32 v22, v22, v20
	s_waitcnt lgkmcnt(0)
	v_max_f32_e32 v20, v20, v22
	v_xor_b32_e32 v22, 128, v21
	ds_bpermute_b32 v22, v22, v20
	s_waitcnt lgkmcnt(0)
	v_max_f32_e32 v20, v20, v22
	v_sub_f32_e32 v20, 0xc2400000, v20
	v_max_f32_e32 v20, 0xc3180000, v20
	v_mul_f32_e32 v200, 0xbfb8aa3b, v4
	v_fmac_f32_e32 v2, v200, v5
	v_cmp_lt_f32_e32 vcc, v20, v2
	s_lshl_b64 s[0:1], 3, s29
	s_or_b64 s[0:1], vcc, s[0:1]
	s_ff1_i32_b64 s4, s[0:1]
	s_flbit_i32_b64 s12, s[0:1]
	s_xor_b32 s11, s12, 63
	s_add_i32 s0, s12, s4
	s_bitcmp0_b32 s0, 0
	s_cbranch_scc1 .LBB0_263
	s_mov_b32 s5, s27
	s_cmp_eq_u64 s[4:5], 0
	s_cbranch_scc1 .LBB0_310
	s_add_i32 s4, s4, -1
	s_cbranch_execnz .LBB0_263
